# GEMM tiles: 112 of the 128 accumulator registers cleared by seven idle-matrix-core MFMAs (0*0+0) instead of v_mov
# baseline (speedup 1.0000x reference)
; #define STAGE(P, BASE, br, kt) STAGET(tid_, P, BASE, br, kt)
; #define WAIT_V(n) asm volatile("s_waitcnt vmcnt(" #n ")" ::: "memory")
; #define BAR __builtin_amdgcn_s_barrier()
; template <int EPI, int K, int KL> ...
;     ...
;   const int wid = tid_ >> 6, lane = tid_ & 63, wr = wid >> 2, wc = wid & 3, fr = lane & 15, fq = lane >> 4;
;   f32x4 acc[2][2][4][2] = {};
;   bf16x8 At[4][2], B0[2][2], B1[2][2];
;   const int nt = KL / BK;
;   if (own_prologue) {
;     STAGE(SB(0, 0), Bt, bcol, 0); STAGE(SA(0, 0), A, brow, 0);
;     STAGE(SB(0, 1), Bt, bcol + HALF, 0); STAGE(SA(0, 1), A, brow + HALF, 0);
;   }
;   if (wr == 1) BAR;
;   WAIT_V(4); BAR;
;   STAGE(SB(1, 0), Bt, bcol, 1); STAGE(SA(1, 0), A, brow, 1); STAGE(SB(1, 1), Bt, bcol + HALF, 1);
;   WAIT_V(6); BAR;
.LBB0_235:
	s_or_b64 exec, exec, s[50:51]
	v_add_u32_e32 v2, v1, v2
	v_and_b32_e32 v2, 0xfffffc00, v2
	v_sub_u32_e32 v2, v1, v2
	v_lshrrev_b32_e32 v5, 4, v2
	v_add_u32_e32 v3, v129, v3
	v_bitop3_b32 v5, v5, v2, 32 bitop3:0x6c
	v_ashrrev_i32_e32 v2, 31, v2
	v_ashrrev_i32_e32 v3, 6, v3
	v_lshrrev_b32_e32 v2, 26, v2
	v_lshlrev_b32_e32 v6, 3, v3
	v_add_u32_e32 v2, v5, v2
	v_and_b32_e32 v6, -16, v6
	v_ashrrev_i32_e32 v7, 6, v2
	v_add_u32_e32 v2, v7, v6
	v_mul_i32_i24_e32 v6, 64, v7
	s_ashr_i32 s47, s46, 31
	v_lshlrev_b32_e32 v3, 5, v3
	v_sub_u32_e32 v5, v5, v6
	s_lshl_b64 s[52:53], s[46:47], 12
	v_readlane_b32 s56, v254, 12
	v_and_b32_e32 v3, 32, v3
	v_ashrrev_i16_sdwa v5, v207, sext(v5) dst_sel:DWORD dst_unused:UNUSED_PAD src0_sel:DWORD src1_sel:BYTE_0
	v_readlane_b32 s57, v254, 13
	s_add_u32 s18, s56, s52
	v_add_u32_sdwa v130, v3, sext(v5) dst_sel:DWORD dst_unused:UNUSED_PAD src0_sel:DWORD src1_sel:WORD_0
	v_ashrrev_i32_e32 v3, 31, v2
	s_addc_u32 s19, s57, s53
	v_lshlrev_b64 v[140:141], 12, v[2:3]
	v_ashrrev_i32_e32 v131, 31, v130
	v_readlane_b32 s47, v254, 45
	v_lshl_add_u64 v[2:3], s[18:19], 0, v[140:141]
	v_lshlrev_b64 v[6:7], 1, v[130:131]
	v_add_u32_e32 v165, s47, v1
	v_lshl_add_u64 v[2:3], v[2:3], 0, v[6:7]
	s_mov_b64 s[58:59], 0x80
	v_readfirstlane_b32 s15, v165
	v_lshl_add_u64 v[2:3], v[2:3], 0, s[58:59]
	s_mov_b32 m0, s15
	s_waitcnt vmcnt(4)
	s_barrier
	global_load_lds_dwordx4 v[2:3], off
	v_ashrrev_i32_e32 v2, 31, v0
	v_lshrrev_b32_e32 v2, 22, v2
	v_add_u32_e32 v2, v0, v2
	v_ashrrev_i32_e32 v3, 10, v2
	v_mul_i32_i24_e32 v2, 0x400, v3
	v_sub_u32_e32 v2, v0, v2
	v_lshrrev_b32_e32 v5, 4, v2
	v_bitop3_b32 v5, v5, v2, 32 bitop3:0x6c
	v_ashrrev_i32_e32 v8, 31, v5
	v_lshrrev_b32_e32 v8, 26, v8
	v_add_u32_e32 v8, v5, v8
	v_lshlrev_b32_e32 v2, 3, v3
	v_ashrrev_i32_e32 v9, 6, v8
	v_and_b32_e32 v8, 0xc0, v8
	v_and_b32_e32 v2, -16, v2
	v_lshlrev_b32_e32 v3, 5, v3
	v_sub_u32_e32 v5, v5, v8
	v_add_u32_e32 v2, v9, v2
	v_and_b32_e32 v3, 32, v3
	v_ashrrev_i16_sdwa v5, v207, sext(v5) dst_sel:DWORD dst_unused:UNUSED_PAD src0_sel:DWORD src1_sel:BYTE_0
	v_add_u32_sdwa v142, v3, sext(v5) dst_sel:DWORD dst_unused:UNUSED_PAD src0_sel:DWORD src1_sel:WORD_0
	v_ashrrev_i32_e32 v3, 31, v2
	v_lshlrev_b64 v[144:145], 12, v[2:3]
	v_ashrrev_i32_e32 v143, 31, v142
	v_lshl_add_u64 v[2:3], s[18:19], 0, v[144:145]
	v_lshlrev_b64 v[8:9], 1, v[142:143]
	v_add_u32_e32 v5, s47, v0
	s_lshl_b64 s[18:19], s[44:45], 12
	v_lshl_add_u64 v[2:3], v[2:3], 0, v[8:9]
	v_readfirstlane_b32 s15, v5
	s_add_u32 s50, s66, s18
	v_lshl_add_u64 v[2:3], v[2:3], 0, s[58:59]
	s_mov_b32 m0, s15
	s_addc_u32 s51, s67, s19
	global_load_lds_dwordx4 v[2:3], off
	v_lshl_add_u64 v[2:3], s[50:51], 0, v[140:141]
	v_add_u32_e32 v166, 0x8000, v157
	v_lshl_add_u64 v[2:3], v[2:3], 0, v[6:7]
	v_readfirstlane_b32 s15, v166
	s_or_b32 s54, s46, 0x80
	v_lshl_add_u64 v[2:3], v[2:3], 0, s[58:59]
	s_mov_b32 m0, s15
	s_ashr_i32 s55, s54, 31
	global_load_lds_dwordx4 v[2:3], off
	v_lshl_add_u64 v[2:3], s[50:51], 0, v[144:145]
	v_add_u32_e32 v167, 0xa000, v157
	s_lshl_b64 s[54:55], s[54:55], 12
	v_lshl_add_u64 v[2:3], v[2:3], 0, v[8:9]
	v_readfirstlane_b32 s15, v167
	s_add_u32 s54, s56, s54
	v_lshl_add_u64 v[2:3], v[2:3], 0, s[58:59]
	s_mov_b32 m0, s15
	s_addc_u32 s55, s57, s55
	v_readlane_b32 s56, v254, 46
	global_load_lds_dwordx4 v[2:3], off
	v_lshl_add_u64 v[2:3], s[54:55], 0, v[140:141]
	v_add_u32_e32 v169, s56, v1
	v_lshl_add_u64 v[2:3], v[2:3], 0, v[6:7]
	v_readfirstlane_b32 s15, v169
	v_lshl_add_u64 v[2:3], v[2:3], 0, s[58:59]
	s_mov_b32 m0, s15
	v_add_u32_e32 v0, s56, v0
	global_load_lds_dwordx4 v[2:3], off
	v_lshl_add_u64 v[2:3], s[54:55], 0, v[144:145]
	v_lshl_add_u64 v[2:3], v[2:3], 0, v[8:9]
	v_readfirstlane_b32 s15, v0
	v_lshl_add_u64 v[2:3], v[2:3], 0, s[58:59]
	s_mov_b32 m0, s15
	v_and_b32_e32 v132, 15, v129
	global_load_lds_dwordx4 v[2:3], off
	v_bfe_u32 v155, v129, 4, 2
	v_lshlrev_b32_e32 v3, 2, v129
	v_lshlrev_b32_e32 v0, 4, v155
	v_lshlrev_b32_e32 v1, 6, v132
	v_and_b32_e32 v3, 32, v3
	v_bitop3_b32 v1, v0, v3, v1 bitop3:0x36
	v_readlane_b32 s15, v254, 43
	v_add_u32_e32 v11, s47, v1
	v_add_u32_e32 v12, s56, v1
	v_add_u32_e32 v5, s15, v1
	v_readlane_b32 s15, v254, 44
	v_add_u32_e32 v13, 0, v1
	v_bfe_u32 v154, v129, 6, 2
	v_add_u32_e32 v10, s15, v1
	v_lshlrev_b32_e32 v1, 6, v129
	s_movk_i32 s15, 0x3c0
	v_and_or_b32 v0, v1, s15, v0
	v_xad_u32 v3, v0, v3, 0
	v_lshl_add_u64 v[0:1], s[52:53], 0, v[140:141]
	v_lshl_add_u64 v[146:147], v[0:1], 0, v[6:7]
	v_lshl_add_u64 v[0:1], s[52:53], 0, v[144:145]
	v_lshl_add_u64 v[148:149], v[0:1], 0, v[8:9]
	v_lshl_add_u64 v[0:1], s[18:19], 0, v[140:141]
	s_waitcnt vmcnt(6)
	v_lshlrev_b32_e32 v128, 6, v4
	v_lshlrev_b32_e32 v4, 13, v4
	v_lshl_add_u64 v[150:151], v[0:1], 0, v[6:7]
	v_lshl_add_u64 v[0:1], s[18:19], 0, v[144:145]
	v_lshlrev_b32_e32 v2, 12, v154
	v_or_b32_e32 v14, 0x800, v4
	v_or_b32_e32 v15, 0x1000, v4
	v_or_b32_e32 v16, 0x1800, v4
	v_lshl_add_u64 v[152:153], v[0:1], 0, v[8:9]
	v_mov_b32_e32 v0, 0
	s_mov_b32 s15, -2
	v_add_u32_e32 v170, v5, v2
	v_add_u32_e32 v162, v13, v4
	v_add_u32_e32 v161, v3, v14
	v_add_u32_e32 v160, v3, v15
	v_add_u32_e32 v159, v3, v16
	v_add_u32_e32 v168, v10, v2
	v_add_u32_e32 v164, v11, v2
	v_add_u32_e32 v163, v12, v2
	s_mov_b64 s[52:53], 0x4300100
	s_mov_b64 s[54:55], 0x4380100
	s_mov_b64 s[56:57], 0x4300180
	s_mov_b64 s[58:59], 0x4380180
	v_mov_b32_e32 v1, v0
	v_mov_b32_e32 v2, v0
	v_mov_b32_e32 v3, v0
	v_mov_b32_e32 v4, v0
	v_mov_b32_e32 v5, v0
	v_mov_b32_e32 v6, v0
	v_mov_b32_e32 v7, v0
	v_mov_b32_e32 v120, v0
	v_mov_b32_e32 v121, v0
	v_mov_b32_e32 v122, v0
	v_mov_b32_e32 v123, v0
	v_mov_b32_e32 v124, v0
	v_mov_b32_e32 v125, v0
	v_mov_b32_e32 v126, v0
	v_mov_b32_e32 v127, v0
	v_mfma_f32_32x32x16_bf16 v[8:23], v[0:3], v[4:7], 0
	v_mfma_f32_32x32x16_bf16 v[24:39], v[0:3], v[4:7], 0
	v_mfma_f32_32x32x16_bf16 v[40:55], v[0:3], v[4:7], 0
	v_mfma_f32_32x32x16_bf16 v[56:71], v[0:3], v[4:7], 0
	v_mfma_f32_32x32x16_bf16 v[72:87], v[0:3], v[4:7], 0
	v_mfma_f32_32x32x16_bf16 v[88:103], v[0:3], v[4:7], 0
	v_mfma_f32_32x32x16_bf16 v[104:119], v[0:3], v[4:7], 0

; #define STAGE(P, BASE, br, kt) STAGET(tid_, P, BASE, br, kt)
; #define WAIT_V(n) asm volatile("s_waitcnt vmcnt(" #n ")" ::: "memory")
; #define BAR __builtin_amdgcn_s_barrier()
; template <int EPI, int K, int KL> ...
;     ...
;   const int wid = tid_ >> 6, lane = tid_ & 63, wr = wid >> 2, wc = wid & 3, fr = lane & 15, fq = lane >> 4;
;   f32x4 acc[2][2][4][2] = {};
;   bf16x8 At[4][2], B0[2][2], B1[2][2];
;   const int nt = KL / BK;
;   if (own_prologue) {
;     STAGE(SB(0, 0), Bt, bcol, 0); STAGE(SA(0, 0), A, brow, 0);
;     STAGE(SB(0, 1), Bt, bcol + HALF, 0); STAGE(SA(0, 1), A, brow + HALF, 0);
;   }
;   if (wr == 1) BAR;
;   WAIT_V(4); BAR;
;   STAGE(SB(1, 0), Bt, bcol, 1); STAGE(SA(1, 0), A, brow, 1); STAGE(SB(1, 1), Bt, bcol + HALF, 1);
;   WAIT_V(6); BAR;
.LBB0_939:
	s_or_b64 exec, exec, s[58:59]
	v_add_u32_e32 v2, v1, v2
	v_and_b32_e32 v2, 0xfffffc00, v2
	v_sub_u32_e32 v2, v1, v2
	v_lshrrev_b32_e32 v5, 4, v2
	v_add_u32_e32 v3, v154, v3
	v_bitop3_b32 v5, v5, v2, 32 bitop3:0x6c
	v_ashrrev_i32_e32 v2, 31, v2
	v_ashrrev_i32_e32 v3, 6, v3
	v_lshrrev_b32_e32 v2, 26, v2
	v_lshlrev_b32_e32 v6, 3, v3
	v_add_u32_e32 v2, v5, v2
	v_and_b32_e32 v6, -16, v6
	v_ashrrev_i32_e32 v7, 6, v2
	v_add_u32_e32 v2, v7, v6
	v_mul_i32_i24_e32 v6, 64, v7
	s_ashr_i32 s55, s54, 31
	v_lshlrev_b32_e32 v3, 5, v3
	v_sub_u32_e32 v5, v5, v6
	s_lshl_b64 s[60:61], s[54:55], 12
	v_readlane_b32 s70, v254, 24
	v_and_b32_e32 v3, 32, v3
	v_ashrrev_i16_sdwa v5, v207, sext(v5) dst_sel:DWORD dst_unused:UNUSED_PAD src0_sel:DWORD src1_sel:BYTE_0
	v_readlane_b32 s71, v254, 25
	s_add_u32 s58, s70, s60
	v_add_u32_sdwa v128, v3, sext(v5) dst_sel:DWORD dst_unused:UNUSED_PAD src0_sel:DWORD src1_sel:WORD_0
	v_ashrrev_i32_e32 v3, 31, v2
	s_addc_u32 s59, s71, s61
	v_lshlrev_b64 v[130:131], 12, v[2:3]
	v_ashrrev_i32_e32 v129, 31, v128
	v_readlane_b32 s73, v254, 45
	v_lshl_add_u64 v[2:3], s[58:59], 0, v[130:131]
	v_lshlrev_b64 v[6:7], 1, v[128:129]
	v_add_u32_e32 v164, s73, v1
	v_lshl_add_u64 v[2:3], v[2:3], 0, v[6:7]
	s_mov_b64 s[74:75], 0x80
	v_readfirstlane_b32 s55, v164
	v_lshl_add_u64 v[2:3], v[2:3], 0, s[74:75]
	s_mov_b32 m0, s55
	s_waitcnt vmcnt(4)
	s_barrier
	global_load_lds_dwordx4 v[2:3], off
	v_ashrrev_i32_e32 v2, 31, v0
	v_lshrrev_b32_e32 v2, 22, v2
	v_add_u32_e32 v2, v0, v2
	v_ashrrev_i32_e32 v3, 10, v2
	v_mul_i32_i24_e32 v2, 0x400, v3
	v_sub_u32_e32 v2, v0, v2
	v_lshrrev_b32_e32 v5, 4, v2
	v_bitop3_b32 v5, v5, v2, 32 bitop3:0x6c
	v_ashrrev_i32_e32 v8, 31, v5
	v_lshrrev_b32_e32 v8, 26, v8
	v_add_u32_e32 v8, v5, v8
	v_lshlrev_b32_e32 v2, 3, v3
	v_ashrrev_i32_e32 v9, 6, v8
	v_and_b32_e32 v8, 0xc0, v8
	v_and_b32_e32 v2, -16, v2
	v_lshlrev_b32_e32 v3, 5, v3
	v_sub_u32_e32 v5, v5, v8
	v_add_u32_e32 v2, v9, v2
	v_and_b32_e32 v3, 32, v3
	v_ashrrev_i16_sdwa v5, v207, sext(v5) dst_sel:DWORD dst_unused:UNUSED_PAD src0_sel:DWORD src1_sel:BYTE_0
	v_add_u32_sdwa v140, v3, sext(v5) dst_sel:DWORD dst_unused:UNUSED_PAD src0_sel:DWORD src1_sel:WORD_0
	v_ashrrev_i32_e32 v3, 31, v2
	v_lshlrev_b64 v[142:143], 12, v[2:3]
	v_ashrrev_i32_e32 v141, 31, v140
	v_lshl_add_u64 v[2:3], s[58:59], 0, v[142:143]
	v_lshlrev_b64 v[8:9], 1, v[140:141]
	v_add_u32_e32 v5, s73, v0
	s_lshl_b64 s[62:63], s[52:53], 12
	v_lshl_add_u64 v[2:3], v[2:3], 0, v[8:9]
	v_readfirstlane_b32 s55, v5
	s_add_u32 s58, s66, s62
	v_lshl_add_u64 v[2:3], v[2:3], 0, s[74:75]
	s_mov_b32 m0, s55
	s_addc_u32 s59, s67, s63
	global_load_lds_dwordx4 v[2:3], off
	v_lshl_add_u64 v[2:3], s[58:59], 0, v[130:131]
	v_add_u32_e32 v166, 0x8000, v157
	v_lshl_add_u64 v[2:3], v[2:3], 0, v[6:7]
	v_readfirstlane_b32 s55, v166
	s_or_b32 s66, s54, 0x80
	v_lshl_add_u64 v[2:3], v[2:3], 0, s[74:75]
	s_mov_b32 m0, s55
	s_ashr_i32 s67, s66, 31
	global_load_lds_dwordx4 v[2:3], off
	v_lshl_add_u64 v[2:3], s[58:59], 0, v[142:143]
	v_add_u32_e32 v167, 0xa000, v157
	s_lshl_b64 s[66:67], s[66:67], 12
	v_lshl_add_u64 v[2:3], v[2:3], 0, v[8:9]
	v_readfirstlane_b32 s55, v167
	s_add_u32 s66, s70, s66
	v_lshl_add_u64 v[2:3], v[2:3], 0, s[74:75]
	s_mov_b32 m0, s55
	s_addc_u32 s67, s71, s67
	v_readlane_b32 s70, v254, 46
	global_load_lds_dwordx4 v[2:3], off
	v_lshl_add_u64 v[2:3], s[66:67], 0, v[130:131]
	v_add_u32_e32 v169, s70, v1
	v_lshl_add_u64 v[2:3], v[2:3], 0, v[6:7]
	v_readfirstlane_b32 s55, v169
	v_lshl_add_u64 v[2:3], v[2:3], 0, s[74:75]
	s_mov_b32 m0, s55
	v_add_u32_e32 v0, s70, v0
	global_load_lds_dwordx4 v[2:3], off
	v_lshl_add_u64 v[2:3], s[66:67], 0, v[142:143]
	v_lshl_add_u64 v[2:3], v[2:3], 0, v[8:9]
	v_readfirstlane_b32 s55, v0
	v_lshl_add_u64 v[2:3], v[2:3], 0, s[74:75]
	s_mov_b32 m0, s55
	v_and_b32_e32 v132, 15, v154
	global_load_lds_dwordx4 v[2:3], off
	v_bfe_u32 v153, v154, 4, 2
	v_lshlrev_b32_e32 v3, 2, v154
	v_lshlrev_b32_e32 v0, 4, v153
	v_lshlrev_b32_e32 v1, 6, v132
	v_and_b32_e32 v3, 32, v3
	v_bitop3_b32 v1, v0, v3, v1 bitop3:0x36
	v_readlane_b32 s55, v254, 43
	v_add_u32_e32 v11, s73, v1
	v_add_u32_e32 v12, s70, v1
	v_add_u32_e32 v5, s55, v1
	v_readlane_b32 s55, v254, 44
	v_add_u32_e32 v13, 0, v1
	v_bfe_u32 v152, v154, 6, 2
	v_add_u32_e32 v10, s55, v1
	v_lshlrev_b32_e32 v1, 6, v154
	s_movk_i32 s55, 0x3c0
	v_and_or_b32 v0, v1, s55, v0
	v_xad_u32 v3, v0, v3, 0
	v_lshl_add_u64 v[0:1], s[60:61], 0, v[130:131]
	v_lshl_add_u64 v[144:145], v[0:1], 0, v[6:7]
	v_lshl_add_u64 v[0:1], s[60:61], 0, v[142:143]
	v_lshl_add_u64 v[146:147], v[0:1], 0, v[8:9]
	v_lshl_add_u64 v[0:1], s[62:63], 0, v[130:131]
	s_waitcnt vmcnt(6)
	v_lshlrev_b32_e32 v155, 6, v4
	v_lshlrev_b32_e32 v4, 13, v4
	v_lshl_add_u64 v[148:149], v[0:1], 0, v[6:7]
	v_lshl_add_u64 v[0:1], s[62:63], 0, v[142:143]
	v_lshlrev_b32_e32 v2, 12, v152
	v_or_b32_e32 v14, 0x800, v4
	v_or_b32_e32 v15, 0x1000, v4
	v_or_b32_e32 v16, 0x1800, v4
	v_lshl_add_u64 v[150:151], v[0:1], 0, v[8:9]
	v_mov_b32_e32 v0, 0
	s_mov_b32 s55, -2
	v_add_u32_e32 v170, v5, v2
	v_add_u32_e32 v162, v13, v4
	v_add_u32_e32 v161, v3, v14
	v_add_u32_e32 v160, v3, v15
	v_add_u32_e32 v159, v3, v16
	v_add_u32_e32 v168, v10, v2
	v_add_u32_e32 v165, v11, v2
	v_add_u32_e32 v163, v12, v2
	s_mov_b64 s[62:63], 0x5f00100
	s_mov_b64 s[66:67], 0x5f80100
	s_mov_b64 s[70:71], 0x5f00180
	s_mov_b64 s[74:75], 0x5f80180
	v_mov_b32_e32 v1, v0
	v_mov_b32_e32 v2, v0
	v_mov_b32_e32 v3, v0
	v_mov_b32_e32 v4, v0
	v_mov_b32_e32 v5, v0
	v_mov_b32_e32 v6, v0
	v_mov_b32_e32 v7, v0
	v_mov_b32_e32 v120, v0
	v_mov_b32_e32 v121, v0
	v_mov_b32_e32 v122, v0
	v_mov_b32_e32 v123, v0
	v_mov_b32_e32 v124, v0
	v_mov_b32_e32 v125, v0
	v_mov_b32_e32 v126, v0
	v_mov_b32_e32 v127, v0
	v_mfma_f32_32x32x16_bf16 v[8:23], v[0:3], v[4:7], 0
	v_mfma_f32_32x32x16_bf16 v[24:39], v[0:3], v[4:7], 0
	v_mfma_f32_32x32x16_bf16 v[40:55], v[0:3], v[4:7], 0
	v_mfma_f32_32x32x16_bf16 v[56:71], v[0:3], v[4:7], 0
	v_mfma_f32_32x32x16_bf16 v[72:87], v[0:3], v[4:7], 0
	v_mfma_f32_32x32x16_bf16 v[88:103], v[0:3], v[4:7], 0
	v_mfma_f32_32x32x16_bf16 v[104:119], v[0:3], v[4:7], 0

; #define STAGE(P, BASE, br, kt) STAGET(tid_, P, BASE, br, kt)
; #define WAIT_V(n) asm volatile("s_waitcnt vmcnt(" #n ")" ::: "memory")
; #define BAR __builtin_amdgcn_s_barrier()
; template <int EPI, int K, int KL> ...
;     ...
;   const int wid = tid_ >> 6, lane = tid_ & 63, wr = wid >> 2, wc = wid & 3, fr = lane & 15, fq = lane >> 4;
;   f32x4 acc[2][2][4][2] = {};
;   bf16x8 At[4][2], B0[2][2], B1[2][2];
;   const int nt = KL / BK;
;   if (own_prologue) {
;     STAGE(SB(0, 0), Bt, bcol, 0); STAGE(SA(0, 0), A, brow, 0);
;     STAGE(SB(0, 1), Bt, bcol + HALF, 0); STAGE(SA(0, 1), A, brow + HALF, 0);
;   }
;   if (wr == 1) BAR;
;   WAIT_V(4); BAR;
;   STAGE(SB(1, 0), Bt, bcol, 1); STAGE(SA(1, 0), A, brow, 1); STAGE(SB(1, 1), Bt, bcol + HALF, 1);
;   WAIT_V(6); BAR;
.LBB0_1106:
	s_or_b64 exec, exec, s[40:41]
	v_add_u32_e32 v2, v1, v2
	v_and_b32_e32 v2, 0xfffffc00, v2
	v_sub_u32_e32 v2, v1, v2
	s_waitcnt vmcnt(0)
	v_lshrrev_b32_e32 v4, 4, v2
	v_add_u32_e32 v3, v152, v3
	v_bitop3_b32 v4, v4, v2, 32 bitop3:0x6c
	v_ashrrev_i32_e32 v2, 31, v2
	v_ashrrev_i32_e32 v3, 6, v3
	v_lshrrev_b32_e32 v2, 26, v2
	v_lshlrev_b32_e32 v5, 3, v3
	v_add_u32_e32 v2, v4, v2
	v_and_b32_e32 v5, -16, v5
	v_ashrrev_i32_e32 v6, 6, v2
	v_add_u32_e32 v2, v6, v5
	v_mul_i32_i24_e32 v5, 64, v6
	s_ashr_i32 s57, s56, 31
	v_lshlrev_b32_e32 v3, 5, v3
	v_sub_u32_e32 v4, v4, v5
	s_lshl_b64 s[58:59], s[56:57], 12
	v_readlane_b32 s70, v254, 20
	v_and_b32_e32 v3, 32, v3
	v_ashrrev_i16_sdwa v4, v207, sext(v4) dst_sel:DWORD dst_unused:UNUSED_PAD src0_sel:DWORD src1_sel:BYTE_0
	v_readlane_b32 s71, v254, 21
	s_add_u32 s40, s70, s58
	v_add_u32_sdwa v128, v3, sext(v4) dst_sel:DWORD dst_unused:UNUSED_PAD src0_sel:DWORD src1_sel:WORD_0
	v_ashrrev_i32_e32 v3, 31, v2
	s_addc_u32 s41, s71, s59
	v_lshlrev_b64 v[130:131], 12, v[2:3]
	v_ashrrev_i32_e32 v129, 31, v128
	v_readlane_b32 s61, v254, 45
	v_lshl_add_u64 v[2:3], s[40:41], 0, v[130:131]
	v_lshlrev_b64 v[4:5], 1, v[128:129]
	v_add_u32_e32 v165, s61, v1
	v_lshl_add_u64 v[2:3], v[2:3], 0, v[4:5]
	s_mov_b64 s[74:75], 0x80
	v_readfirstlane_b32 s53, v165
	v_lshl_add_u64 v[2:3], v[2:3], 0, s[74:75]
	s_mov_b32 m0, s53
	s_waitcnt vmcnt(4)
	s_barrier
	global_load_lds_dwordx4 v[2:3], off
	v_ashrrev_i32_e32 v2, 31, v0
	v_lshrrev_b32_e32 v2, 22, v2
	v_add_u32_e32 v2, v0, v2
	v_ashrrev_i32_e32 v3, 10, v2
	v_mul_i32_i24_e32 v2, 0x400, v3
	v_sub_u32_e32 v2, v0, v2
	v_lshrrev_b32_e32 v6, 4, v2
	v_bitop3_b32 v6, v6, v2, 32 bitop3:0x6c
	v_ashrrev_i32_e32 v7, 31, v6
	v_lshrrev_b32_e32 v7, 26, v7
	v_add_u32_e32 v7, v6, v7
	v_lshlrev_b32_e32 v2, 3, v3
	v_ashrrev_i32_e32 v8, 6, v7
	v_and_b32_e32 v7, 0xc0, v7
	v_and_b32_e32 v2, -16, v2
	v_lshlrev_b32_e32 v3, 5, v3
	v_sub_u32_e32 v6, v6, v7
	v_add_u32_e32 v2, v8, v2
	v_and_b32_e32 v3, 32, v3
	v_ashrrev_i16_sdwa v6, v207, sext(v6) dst_sel:DWORD dst_unused:UNUSED_PAD src0_sel:DWORD src1_sel:BYTE_0
	v_add_u32_sdwa v140, v3, sext(v6) dst_sel:DWORD dst_unused:UNUSED_PAD src0_sel:DWORD src1_sel:WORD_0
	v_ashrrev_i32_e32 v3, 31, v2
	v_lshlrev_b64 v[142:143], 12, v[2:3]
	v_ashrrev_i32_e32 v141, 31, v140
	v_add_u32_e32 v8, s61, v0
	v_lshl_add_u64 v[2:3], s[40:41], 0, v[142:143]
	v_lshlrev_b64 v[6:7], 1, v[140:141]
	v_readfirstlane_b32 s40, v8
	s_lshl_b64 s[62:63], s[42:43], 12
	v_lshl_add_u64 v[2:3], v[2:3], 0, v[6:7]
	s_mov_b32 m0, s40
	s_add_u32 s40, s66, s62
	v_lshl_add_u64 v[2:3], v[2:3], 0, s[74:75]
	s_addc_u32 s41, s67, s63
	global_load_lds_dwordx4 v[2:3], off
	v_lshl_add_u64 v[2:3], s[40:41], 0, v[130:131]
	v_add_u32_e32 v167, 0x8000, v158
	v_lshl_add_u64 v[2:3], v[2:3], 0, v[4:5]
	v_readfirstlane_b32 s53, v167
	s_bitset1_b32 s56, 7
	v_lshl_add_u64 v[2:3], v[2:3], 0, s[74:75]
	s_mov_b32 m0, s53
	s_ashr_i32 s57, s56, 31
	global_load_lds_dwordx4 v[2:3], off
	v_lshl_add_u64 v[2:3], s[40:41], 0, v[142:143]
	v_add_u32_e32 v168, 0xa000, v158
	s_lshl_b64 s[56:57], s[56:57], 12
	v_lshl_add_u64 v[2:3], v[2:3], 0, v[6:7]
	v_readfirstlane_b32 s53, v168
	s_add_u32 s56, s70, s56
	v_lshl_add_u64 v[2:3], v[2:3], 0, s[74:75]
	s_mov_b32 m0, s53
	s_addc_u32 s57, s71, s57
	v_readlane_b32 s70, v254, 46
	global_load_lds_dwordx4 v[2:3], off
	v_lshl_add_u64 v[2:3], s[56:57], 0, v[130:131]
	v_add_u32_e32 v170, s70, v1
	v_lshl_add_u64 v[2:3], v[2:3], 0, v[4:5]
	v_readfirstlane_b32 s53, v170
	v_lshl_add_u64 v[2:3], v[2:3], 0, s[74:75]
	s_mov_b32 m0, s53
	v_add_u32_e32 v0, s70, v0
	global_load_lds_dwordx4 v[2:3], off
	v_lshl_add_u64 v[2:3], s[56:57], 0, v[142:143]
	v_lshl_add_u64 v[2:3], v[2:3], 0, v[6:7]
	v_readfirstlane_b32 s53, v0
	v_lshl_add_u64 v[2:3], v[2:3], 0, s[74:75]
	s_mov_b32 m0, s53
	v_and_b32_e32 v154, 15, v152
	global_load_lds_dwordx4 v[2:3], off
	v_lshlrev_b32_e32 v132, 2, v152
	v_and_b32_e32 v156, 48, v152
	v_lshlrev_b32_e32 v0, 6, v154
	v_and_b32_e32 v1, 32, v132
	v_bitop3_b32 v0, v0, v1, v156 bitop3:0x36
	v_readlane_b32 s53, v254, 43
	v_add_u32_e32 v9, s61, v0
	v_add_u32_e32 v10, s70, v0
	v_add_u32_e32 v3, s53, v0
	v_readlane_b32 s53, v254, 44
	v_add_u32_e32 v12, 0, v0
	v_bfe_u32 v155, v152, 6, 2
	v_add_u32_e32 v8, s53, v0
	v_lshlrev_b32_e32 v0, 6, v152
	s_movk_i32 s53, 0x3c0
	v_and_or_b32 v0, v0, s53, v156
	v_xad_u32 v13, v0, v1, 0
	v_lshl_add_u64 v[0:1], s[58:59], 0, v[130:131]
	v_lshl_add_u64 v[144:145], v[0:1], 0, v[4:5]
	v_lshl_add_u64 v[0:1], s[58:59], 0, v[142:143]
	v_lshl_add_u64 v[146:147], v[0:1], 0, v[6:7]
	v_lshl_add_u64 v[0:1], s[62:63], 0, v[130:131]
	s_waitcnt vmcnt(6)
	v_lshlrev_b32_e32 v11, 13, v153
	v_lshl_add_u64 v[148:149], v[0:1], 0, v[4:5]
	v_lshl_add_u64 v[0:1], s[62:63], 0, v[142:143]
	v_lshlrev_b32_e32 v2, 12, v155
	v_or_b32_e32 v14, 0x800, v11
	v_or_b32_e32 v15, 0x1000, v11
	v_or_b32_e32 v16, 0x1800, v11
	v_lshl_add_u64 v[150:151], v[0:1], 0, v[6:7]
	v_mov_b32_e32 v0, 0
	s_mov_b32 s53, -2
	v_add_u32_e32 v171, v3, v2
	v_add_u32_e32 v163, v12, v11
	v_add_u32_e32 v162, v13, v14
	v_add_u32_e32 v161, v13, v15
	v_add_u32_e32 v160, v13, v16
	v_add_u32_e32 v169, v8, v2
	v_add_u32_e32 v166, v9, v2
	v_add_u32_e32 v164, v10, v2
	v_mov_b32_e32 v1, v0
	v_mov_b32_e32 v2, v0
	v_mov_b32_e32 v3, v0
	v_mov_b32_e32 v4, v0
	v_mov_b32_e32 v5, v0
	v_mov_b32_e32 v6, v0
	v_mov_b32_e32 v7, v0
	v_mov_b32_e32 v120, v0
	v_mov_b32_e32 v121, v0
	v_mov_b32_e32 v122, v0
	v_mov_b32_e32 v123, v0
	v_mov_b32_e32 v124, v0
	v_mov_b32_e32 v125, v0
	v_mov_b32_e32 v126, v0
	v_mov_b32_e32 v127, v0
	v_mfma_f32_32x32x16_bf16 v[8:23], v[0:3], v[4:7], 0
	v_mfma_f32_32x32x16_bf16 v[24:39], v[0:3], v[4:7], 0
	v_mfma_f32_32x32x16_bf16 v[40:55], v[0:3], v[4:7], 0
	v_mfma_f32_32x32x16_bf16 v[56:71], v[0:3], v[4:7], 0
	v_mfma_f32_32x32x16_bf16 v[72:87], v[0:3], v[4:7], 0
	v_mfma_f32_32x32x16_bf16 v[88:103], v[0:3], v[4:7], 0
	v_mfma_f32_32x32x16_bf16 v[104:119], v[0:3], v[4:7], 0

; #define STAGE(P, BASE, br, kt) STAGET(tid_, P, BASE, br, kt)
; #define WAIT_V(n) asm volatile("s_waitcnt vmcnt(" #n ")" ::: "memory")
; #define BAR __builtin_amdgcn_s_barrier()
; template <int EPI, int K, int KL> ...
;     ...
;   const int wid = tid_ >> 6, lane = tid_ & 63, wr = wid >> 2, wc = wid & 3, fr = lane & 15, fq = lane >> 4;
;   f32x4 acc[2][2][4][2] = {};
;   bf16x8 At[4][2], B0[2][2], B1[2][2];
;   const int nt = KL / BK;
;   if (own_prologue) {
;     STAGE(SB(0, 0), Bt, bcol, 0); STAGE(SA(0, 0), A, brow, 0);
;     STAGE(SB(0, 1), Bt, bcol + HALF, 0); STAGE(SA(0, 1), A, brow + HALF, 0);
;   }
;   if (wr == 1) BAR;
;   WAIT_V(4); BAR;
;   STAGE(SB(1, 0), Bt, bcol, 1); STAGE(SA(1, 0), A, brow, 1); STAGE(SB(1, 1), Bt, bcol + HALF, 1);
;   WAIT_V(6); BAR;
.LBB0_1183:
	s_or_b64 exec, exec, s[52:53]
	v_add_u32_e32 v2, v0, v2
	v_and_b32_e32 v2, 0xfffffc00, v2
	v_sub_u32_e32 v2, v0, v2
	v_lshrrev_b32_e32 v5, 4, v2
	v_add_u32_e32 v3, v154, v3
	v_bitop3_b32 v5, v5, v2, 32 bitop3:0x6c
	v_ashrrev_i32_e32 v2, 31, v2
	v_ashrrev_i32_e32 v3, 6, v3
	v_lshrrev_b32_e32 v2, 26, v2
	v_lshlrev_b32_e32 v6, 3, v3
	v_add_u32_e32 v2, v5, v2
	v_and_b32_e32 v6, -16, v6
	v_ashrrev_i32_e32 v2, 6, v2
	v_add_u32_e32 v12, v2, v6
	v_mul_i32_i24_e32 v2, 64, v2
	v_readlane_b32 s58, v254, 22
	v_lshlrev_b32_e32 v3, 5, v3
	v_sub_u32_e32 v2, v5, v2
	v_readlane_b32 s59, v254, 23
	s_add_u32 s52, s58, s57
	v_and_b32_e32 v3, 32, v3
	v_ashrrev_i16_sdwa v2, v207, sext(v2) dst_sel:DWORD dst_unused:UNUSED_PAD src0_sel:DWORD src1_sel:BYTE_0
	s_movk_i32 s60, 0x2c00
	s_addc_u32 s53, s59, s56
	v_add_u32_sdwa v128, v3, sext(v2) dst_sel:DWORD dst_unused:UNUSED_PAD src0_sel:DWORD src1_sel:WORD_0
	v_mad_i64_i32 v[130:131], s[56:57], v12, s60, 0
	v_mov_b64_e32 v[2:3], s[52:53]
	v_ashrrev_i32_e32 v129, 31, v128
	v_readlane_b32 s56, v254, 45
	v_ashrrev_i32_e32 v5, 31, v1
	v_mad_i64_i32 v[6:7], s[52:53], v12, s60, v[2:3]
	v_lshlrev_b64 v[8:9], 1, v[128:129]
	v_add_u32_e32 v164, s56, v0
	v_lshrrev_b32_e32 v5, 22, v5
	v_lshl_add_u64 v[6:7], v[6:7], 0, v[8:9]
	s_mov_b64 s[64:65], 0x80
	v_readfirstlane_b32 s52, v164
	v_add_u32_e32 v5, v1, v5
	v_lshl_add_u64 v[6:7], v[6:7], 0, s[64:65]
	s_mov_b32 m0, s52
	v_ashrrev_i32_e32 v5, 10, v5
	s_waitcnt vmcnt(4)
	s_barrier
	global_load_lds_dwordx4 v[6:7], off
	v_mul_i32_i24_e32 v6, 0x400, v5
	v_sub_u32_e32 v6, v1, v6
	v_lshrrev_b32_e32 v7, 4, v6
	v_bitop3_b32 v6, v7, v6, 32 bitop3:0x6c
	v_ashrrev_i32_e32 v10, 31, v6
	v_lshrrev_b32_e32 v10, 26, v10
	v_lshlrev_b32_e32 v7, 3, v5
	v_add_u32_e32 v10, v6, v10
	v_and_b32_e32 v7, -16, v7
	v_ashrrev_i32_e32 v11, 6, v10
	v_add_u32_e32 v13, v11, v7
	v_and_b32_e32 v7, 0xc0, v10
	v_lshlrev_b32_e32 v5, 5, v5
	v_sub_u32_e32 v6, v6, v7
	v_and_b32_e32 v5, 32, v5
	v_ashrrev_i16_sdwa v6, v207, sext(v6) dst_sel:DWORD dst_unused:UNUSED_PAD src0_sel:DWORD src1_sel:BYTE_0
	v_add_u32_sdwa v140, v5, sext(v6) dst_sel:DWORD dst_unused:UNUSED_PAD src0_sel:DWORD src1_sel:WORD_0
	v_mad_i64_i32 v[142:143], s[52:53], v13, s60, 0
	v_mad_i64_i32 v[2:3], s[52:53], v13, s60, v[2:3]
	v_ashrrev_i32_e32 v141, 31, v140
	v_add_u32_e32 v5, s56, v1
	v_lshlrev_b64 v[6:7], 1, v[140:141]
	v_readfirstlane_b32 s52, v5
	s_add_i32 s54, s54, s19
	v_lshl_add_u64 v[2:3], v[2:3], 0, v[6:7]
	s_mov_b32 m0, s52
	s_add_u32 s52, s62, s55
	v_lshl_add_u64 v[2:3], v[2:3], 0, s[64:65]
	s_addc_u32 s53, s63, s54
	global_load_lds_dwordx4 v[2:3], off
	v_mov_b64_e32 v[2:3], s[52:53]
	v_mad_i64_i32 v[10:11], s[54:55], v12, s60, v[2:3]
	v_add_u32_e32 v166, 0x8000, v157
	v_lshl_add_u64 v[10:11], v[10:11], 0, v[8:9]
	v_readfirstlane_b32 s54, v166
	s_mov_b32 m0, s54
	v_mad_i64_i32 v[2:3], s[54:55], v13, s60, v[2:3]
	v_add_u32_e32 v167, 0xa000, v157
	v_lshl_add_u64 v[10:11], v[10:11], 0, s[64:65]
	v_readfirstlane_b32 s54, v167
	global_load_lds_dwordx4 v[10:11], off
	s_mov_b32 m0, s54
	s_or_b32 s54, s18, 0x80
	s_mul_hi_i32 s55, s54, 0x2c00
	s_mulk_i32 s54, 0x2c00
	v_lshl_add_u64 v[2:3], v[2:3], 0, v[6:7]
	s_add_u32 s54, s58, s54
	v_lshl_add_u64 v[2:3], v[2:3], 0, s[64:65]
	s_addc_u32 s55, s59, s55
	global_load_lds_dwordx4 v[2:3], off
	v_mov_b64_e32 v[2:3], s[54:55]
	v_readlane_b32 s57, v254, 46
	v_mad_i64_i32 v[10:11], s[54:55], v12, s60, v[2:3]
	s_nop 0
	v_add_u32_e32 v168, s57, v0
	v_lshl_add_u64 v[10:11], v[10:11], 0, v[8:9]
	v_readfirstlane_b32 s54, v168
	s_mov_b32 m0, s54
	v_mad_i64_i32 v[2:3], s[54:55], v13, s60, v[2:3]
	v_add_u32_e32 v0, s57, v1
	v_lshl_add_u64 v[10:11], v[10:11], 0, s[64:65]
	v_lshl_add_u64 v[2:3], v[2:3], 0, v[6:7]
	v_readfirstlane_b32 s54, v0
	global_load_lds_dwordx4 v[10:11], off
	v_lshl_add_u64 v[2:3], v[2:3], 0, s[64:65]
	s_mov_b32 m0, s54
	v_and_b32_e32 v132, 15, v154
	global_load_lds_dwordx4 v[2:3], off
	v_bfe_u32 v153, v154, 4, 2
	v_lshlrev_b32_e32 v3, 2, v154
	v_lshlrev_b32_e32 v0, 4, v153
	v_lshlrev_b32_e32 v1, 6, v132
	v_and_b32_e32 v3, 32, v3
	v_bitop3_b32 v1, v0, v3, v1 bitop3:0x36
	v_readlane_b32 s54, v254, 43
	v_add_u32_e32 v11, s56, v1
	v_add_u32_e32 v12, s57, v1
	v_add_u32_e32 v5, s54, v1
	v_readlane_b32 s54, v254, 44
	v_add_u32_e32 v13, 0, v1
	v_bfe_u32 v152, v154, 6, 2
	v_add_u32_e32 v10, s54, v1
	v_lshlrev_b32_e32 v1, 6, v154
	s_movk_i32 s54, 0x3c0
	v_and_or_b32 v0, v1, s54, v0
	v_xad_u32 v3, v0, v3, 0
	v_mad_i64_i32 v[0:1], s[54:55], s18, v250, v[130:131]
	v_lshl_add_u64 v[144:145], v[0:1], 0, v[8:9]
	v_mad_i64_i32 v[0:1], s[54:55], s18, v250, v[142:143]
	v_lshl_add_u64 v[146:147], v[0:1], 0, v[6:7]
	v_mad_u64_u32 v[0:1], s[54:55], s48, v250, v[130:131]
	v_add_u32_e32 v1, s19, v1
	v_lshl_add_u64 v[148:149], v[0:1], 0, v[8:9]
	v_mad_u64_u32 v[0:1], s[54:55], s48, v250, v[142:143]
	s_waitcnt vmcnt(6)
	v_lshlrev_b32_e32 v155, 6, v4
	v_lshlrev_b32_e32 v4, 13, v4
	v_add_u32_e32 v1, s19, v1
	v_lshlrev_b32_e32 v2, 12, v152
	v_or_b32_e32 v14, 0x800, v4
	v_or_b32_e32 v15, 0x1000, v4
	v_or_b32_e32 v16, 0x1800, v4
	v_lshl_add_u64 v[150:151], v[0:1], 0, v[6:7]
	v_mov_b32_e32 v0, 0
	s_mov_b32 s19, -2
	v_add_u32_e32 v170, v5, v2
	v_add_u32_e32 v162, v13, v4
	v_add_u32_e32 v161, v3, v14
	v_add_u32_e32 v160, v3, v15
	v_add_u32_e32 v159, v3, v16
	v_add_u32_e32 v169, v10, v2
	v_add_u32_e32 v165, v11, v2
	v_add_u32_e32 v163, v12, v2
	v_mov_b32_e32 v1, v0
	v_mov_b32_e32 v2, v0
	v_mov_b32_e32 v3, v0
	v_mov_b32_e32 v4, v0
	v_mov_b32_e32 v5, v0
	v_mov_b32_e32 v6, v0
	v_mov_b32_e32 v7, v0
	v_mov_b32_e32 v120, v0
	v_mov_b32_e32 v121, v0
	v_mov_b32_e32 v122, v0
	v_mov_b32_e32 v123, v0
	v_mov_b32_e32 v124, v0
	v_mov_b32_e32 v125, v0
	v_mov_b32_e32 v126, v0
	v_mov_b32_e32 v127, v0
	v_mfma_f32_32x32x16_bf16 v[8:23], v[0:3], v[4:7], 0
	v_mfma_f32_32x32x16_bf16 v[24:39], v[0:3], v[4:7], 0
	v_mfma_f32_32x32x16_bf16 v[40:55], v[0:3], v[4:7], 0
	v_mfma_f32_32x32x16_bf16 v[56:71], v[0:3], v[4:7], 0
	v_mfma_f32_32x32x16_bf16 v[72:87], v[0:3], v[4:7], 0
	v_mfma_f32_32x32x16_bf16 v[88:103], v[0:3], v[4:7], 0
	v_mfma_f32_32x32x16_bf16 v[104:119], v[0:3], v[4:7], 0

; #define STAGE(P, BASE, br, kt) STAGET(tid_, P, BASE, br, kt)
; #define WAIT_V(n) asm volatile("s_waitcnt vmcnt(" #n ")" ::: "memory")
; #define BAR __builtin_amdgcn_s_barrier()
; template <int EPI, int K, int KL> ...
;     ...
;   const int wid = tid_ >> 6, lane = tid_ & 63, wr = wid >> 2, wc = wid & 3, fr = lane & 15, fq = lane >> 4;
;   f32x4 acc[2][2][4][2] = {};
;   bf16x8 At[4][2], B0[2][2], B1[2][2];
;   const int nt = KL / BK;
;   if (own_prologue) {
;     STAGE(SB(0, 0), Bt, bcol, 0); STAGE(SA(0, 0), A, brow, 0);
;     STAGE(SB(0, 1), Bt, bcol + HALF, 0); STAGE(SA(0, 1), A, brow + HALF, 0);
;   }
;   if (wr == 1) BAR;
;   WAIT_V(4); BAR;
;   STAGE(SB(1, 0), Bt, bcol, 1); STAGE(SA(1, 0), A, brow, 1); STAGE(SB(1, 1), Bt, bcol + HALF, 1);
;   WAIT_V(6); BAR;
; __device__ __forceinline__ void gemm_ctx_splitk_down(const u16* A, const u16* Bt, float* P2, const EpiArgs& e0) {
;     ...
;   for (int u = bid_; u < 16 * P2_PARTS; u += gridDim.x) {
;     const int tile = u / P2_PARTS, part = u % P2_PARTS, pm = 128 + (tile >> 3), pn = tile & 7;
;     EpiArgs e = e0; e.part = P2 + (size_t)part * 512 * DM;
;     const long koff = (long)part * (DFF / P2_PARTS);
;     gemm_tile<EPI_PART, DFF, DFF / P2_PARTS>(A + koff, Bt + koff, (long)pm * BM, pn * BM, pn, 0, 0, e, true, false, 0, 0);
.LBB0_1203:
	s_or_b64 exec, exec, s[50:51]
	s_movk_i32 s50, 0x2c00
	v_mad_i64_i32 v[142:143], s[18:19], v13, s50, 0
	v_mad_i64_i32 v[140:141], s[18:19], v15, s50, 0
	v_readlane_b32 s50, v254, 45
	s_mov_b64 s[56:57], 0x80
	v_lshl_add_u64 v[4:5], v[4:5], 0, s[56:57]
	v_add_u32_e32 v168, s50, v12
	v_add_u32_e32 v169, 0x2000, v168
	v_readfirstlane_b32 s18, v168
	s_mov_b32 m0, s18
	v_readfirstlane_b32 s18, v169
	v_add_u32_e32 v170, 0x8000, v161
	s_waitcnt vmcnt(4)
	s_barrier
	global_load_lds_dwordx4 v[4:5], off
	v_lshl_add_u64 v[4:5], v[6:7], 0, s[56:57]
	s_mov_b32 m0, s18
	v_readfirstlane_b32 s18, v170
	v_add_u32_e32 v171, 0xa000, v161
	global_load_lds_dwordx4 v[4:5], off
	v_lshl_add_u64 v[4:5], v[8:9], 0, s[56:57]
	s_mov_b32 m0, s18
	v_readfirstlane_b32 s18, v171
	global_load_lds_dwordx4 v[4:5], off
	s_mov_b32 m0, s18
	s_add_u32 s18, s48, 0x160080
	s_addc_u32 s19, s49, 0
	v_readlane_b32 s49, v254, 46
	v_lshl_add_u64 v[4:5], v[10:11], 0, s[56:57]
	global_load_lds_dwordx4 v[4:5], off
	v_add_u32_e32 v172, s49, v12
	v_lshl_add_u64 v[4:5], s[18:19], 0, v[142:143]
	v_readfirstlane_b32 s48, v172
	v_lshl_add_u64 v[4:5], v[4:5], 0, v[0:1]
	s_mov_b32 m0, s48
	v_add_u32_e32 v174, 0x2000, v172
	global_load_lds_dwordx4 v[4:5], off
	v_lshl_add_u64 v[4:5], s[18:19], 0, v[140:141]
	v_readfirstlane_b32 s18, v174
	v_lshl_add_u64 v[4:5], v[4:5], 0, v[2:3]
	s_mov_b32 m0, s18
	v_and_b32_e32 v251, 15, v132
	global_load_lds_dwordx4 v[4:5], off
	v_bfe_u32 v252, v132, 4, 2
	v_lshlrev_b32_e32 v7, 2, v132
	v_lshlrev_b32_e32 v4, 4, v252
	v_lshlrev_b32_e32 v5, 6, v251
	v_and_b32_e32 v7, 32, v7
	v_bitop3_b32 v5, v4, v7, v5 bitop3:0x36
	v_readlane_b32 s18, v254, 43
	v_add_u32_e32 v10, s50, v5
	v_add_u32_e32 v11, s49, v5
	v_add_u32_e32 v8, s18, v5
	v_readlane_b32 s18, v254, 44
	v_add_u32_e32 v13, 0, v5
	s_and_b32 s15, s15, 7
	v_add_u32_e32 v9, s18, v5
	v_lshlrev_b32_e32 v5, 6, v132
	s_movk_i32 s18, 0x3c0
	v_and_or_b32 v4, v5, s18, v4
	v_mov_b32_e32 v17, 0x2c0000
	v_xad_u32 v7, v4, v7, 0
	v_mad_u64_u32 v[4:5], s[18:19], s15, v17, v[142:143]
	v_lshl_add_u64 v[4:5], v[4:5], 0, v[0:1]
	v_lshl_add_u64 v[144:145], s[92:93], 0, v[4:5]
	v_mad_u64_u32 v[4:5], s[18:19], s15, v17, v[140:141]
	v_lshl_add_u64 v[4:5], v[4:5], 0, v[2:3]
	v_lshl_add_u64 v[146:147], s[92:93], 0, v[4:5]
	v_mad_i64_i32 v[4:5], s[18:19], s14, v17, v[142:143]
	v_lshl_add_u64 v[0:1], v[4:5], 0, v[0:1]
	v_lshl_add_u64 v[148:149], s[92:93], 0, v[0:1]
	v_mad_i64_i32 v[0:1], s[14:15], s14, v17, v[140:141]
	v_bfe_u32 v206, v132, 6, 2
	s_waitcnt vmcnt(6)
	v_lshlrev_b32_e32 v12, 13, v14
	v_lshl_add_u64 v[0:1], v[0:1], 0, v[2:3]
	v_lshlrev_b32_e32 v6, 12, v206
	v_lshlrev_b32_e32 v134, 6, v14
	v_or_b32_e32 v14, 0x800, v12
	v_or_b32_e32 v15, 0x1000, v12
	v_or_b32_e32 v16, 0x1800, v12
	v_lshl_add_u64 v[150:151], s[92:93], 0, v[0:1]
	v_mov_b32_e32 v0, 0
	s_mov_b32 s14, -2
	v_add_u32_e32 v175, v8, v6
	v_add_u32_e32 v160, v13, v12
	v_add_u32_e32 v159, v7, v14
	v_add_u32_e32 v158, v7, v15
	v_add_u32_e32 v157, v7, v16
	v_add_u32_e32 v173, v9, v6
	v_add_u32_e32 v166, v10, v6
	v_add_u32_e32 v163, v11, v6
	s_waitcnt vmcnt(0)
	v_mov_b32_e32 v1, v0
	v_mov_b32_e32 v2, v0
	v_mov_b32_e32 v3, v0
	v_mov_b32_e32 v4, v0
	v_mov_b32_e32 v5, v0
	v_mov_b32_e32 v6, v0
	v_mov_b32_e32 v7, v0
	v_mov_b32_e32 v120, v0
	v_mov_b32_e32 v121, v0
	v_mov_b32_e32 v122, v0
	v_mov_b32_e32 v123, v0
	v_mov_b32_e32 v124, v0
	v_mov_b32_e32 v125, v0
	v_mov_b32_e32 v126, v0
	v_mov_b32_e32 v127, v0
	v_mfma_f32_32x32x16_bf16 v[8:23], v[0:3], v[4:7], 0
	v_mfma_f32_32x32x16_bf16 v[24:39], v[0:3], v[4:7], 0
	v_mfma_f32_32x32x16_bf16 v[40:55], v[0:3], v[4:7], 0
	v_mfma_f32_32x32x16_bf16 v[56:71], v[0:3], v[4:7], 0
	v_mfma_f32_32x32x16_bf16 v[72:87], v[0:3], v[4:7], 0
	v_mfma_f32_32x32x16_bf16 v[88:103], v[0:3], v[4:7], 0
	v_mfma_f32_32x32x16_bf16 v[104:119], v[0:3], v[4:7], 0
